# k32: k20 + static s_setprio 1 for waves 4-7 during the retention scan (lockstep same-program waves, MICROARCH item 9 de-phasing)
# baseline (speedup 1.0000x reference)
; __device__ __forceinline__ int opaque_tid() { int t = threadIdx.x; asm volatile("" : "+v"(t)); return t; }
; __device__ void ret_phase(const Params& p, unsigned char* ldsb, int lj, int half) {
;     const int tid0 = opaque_tid(), w = __builtin_amdgcn_readfirstlane(tid0 >> 6), lane0 = tid0 & 63, r0_ = lane0 & 15, g0_ = lane0 >> 4;
;     bf16_t* Qs = (bf16_t*)ldsb;
;     bf16_t* Ks = Qs + 64 * QS_LD;
;     bf16_t* Ps = Ks + 64 * KS_LD;
;     bf16_t* Vl = Ps + 64 * P_LD;
;     bf16_t* Qp = Vl + 64 * VS_LD;
;     const bf16_t* Qg = (const bf16_t*)(p.ws + WS_R1);
;     const bf16_t* Kg = Qg + (size_t)TH * 1024;
;     const bf16_t* Vg = Kg + (size_t)TH * 1024;
;     bf16_t* Y = (bf16_t*)(p.ws + WS_Y);
;     const int jb = w & 3, ih = w >> 2;
.LBB0_375:
	s_or_b64 exec, exec, s[2:3]
	v_readlane_b32 s0, v254, 34
	v_mov_b32_e32 v186, v210
	v_readlane_b32 s1, v254, 35
	s_xor_b64 s[14:15], s[16:17], -1
	s_barrier
	s_andn2_b64 vcc, exec, s[0:1]
	v_readfirstlane_b32 s0, v186
	s_cbranch_vccnz .LBB0_450
	v_lshlrev_b32_e32 v2, 4, v186
	v_lshlrev_b32_e32 v1, 6, v186
	v_and_b32_e32 v3, 0x1f0, v2
	s_movk_i32 s1, 0xf800
	v_and_b32_e32 v187, 15, v186
	s_ashr_i32 s0, s0, 6
	s_cmp_gt_u32 s0, 3
	s_cbranch_scc0 .Lret_prio_skip
	s_setprio 1
.Lret_prio_skip:
	v_and_or_b32 v156, v1, s1, v3
	v_lshlrev_b32_e32 v1, 8, v186
	v_and_b32_e32 v2, 0xf0, v2
	v_bfe_u32 v188, v186, 4, 2
	v_and_or_b32 v158, v1, s36, v2
	v_lshlrev_b32_e32 v1, 12, v187
	s_lshl_b32 s16, s0, 4
	s_lshl_b32 s71, s0, 3
	v_lshl_or_b32 v160, v188, 3, v1
	v_mov_b32_e32 v157, v0
	v_mov_b32_e32 v159, v0
	s_and_b32 s70, s16, 48
	s_andn2_b32 s71, s71, 31
	s_ashr_i32 s17, s16, 31
	v_mov_b32_e32 v161, v0
	s_mov_b32 s18, s37

; __device__ __forceinline__ void gbar(unsigned* ctr, unsigned& target) {
;     asm volatile("s_waitcnt vmcnt(0) lgkmcnt(0)" ::: "memory");
;     __syncthreads();
;     target += gridDim.x;
;     if (threadIdx.x == 0) {
;         __builtin_amdgcn_fence(__ATOMIC_RELEASE, "agent");
;         asm volatile("s_waitcnt vmcnt(0)" ::: "memory");
;         __hip_atomic_fetch_add(ctr, 1u, __ATOMIC_RELAXED, __HIP_MEMORY_SCOPE_AGENT);
;         while (__hip_atomic_load(ctr, __ATOMIC_RELAXED, __HIP_MEMORY_SCOPE_AGENT) < target) __builtin_amdgcn_s_sleep(2);
.LBB0_450:
	s_setprio 0
	s_waitcnt vmcnt(0) lgkmcnt(0)
	s_add_i32 s88, s69, s90
	s_barrier
	s_mov_b64 s[2:3], exec
	v_readlane_b32 s0, v255, 1
	v_readlane_b32 s1, v255, 2
	s_and_b64 s[0:1], s[2:3], s[0:1]
	s_mov_b64 exec, s[0:1]
	s_cbranch_execz .LBB0_320
	s_mov_b64 s[4:5], exec
	buffer_wbl2 sc1
	s_waitcnt vmcnt(0)
	s_waitcnt vmcnt(0)
	v_mbcnt_lo_u32_b32 v1, s4, 0
	v_mbcnt_hi_u32_b32 v1, s5, v1
	v_cmp_eq_u32_e32 vcc, 0, v1
	s_and_saveexec_b64 s[16:17], vcc
	s_cbranch_execz .LBB0_453
	s_bcnt1_i32_b64 s0, s[4:5]
	v_mov_b32_e32 v1, s0
	global_atomic_add v0, v1, s[42:43]
